# MLP-up epilogue: redundant canonicalizing max folded into the ReLU max (98 fewer VALU per unit), store-data wait states restored with s_nop
# baseline (speedup 1.0000x reference)
; __device__ __forceinline__ u32x2 pk4(f32x4 v) { u32x2 w; w.x = cvt_pk_bf16(v[0], v[1]); w.y = cvt_pk_bf16(v[2], v[3]); return w; }
; #define EPI_ROWS(ai, m) _Pragma("unroll") for (int ai = 0; ai < 2; ++ai) _Pragma("unroll") for (int m = 0; m < 4; ++m)
;     __device__ __forceinline__ void operator()(const Acc& acc, const Unit& u, int wr, int wc, int fr, int fq) const {
;         EPI_ROWS(ai, m) { const int row = u.pm * 256 + ai * 128 + wr * 64 + m * 16 + fr;
; #pragma unroll
;             for (int bj = 0; bj < 2; ++bj) { const int col = u.pn * 256 + bj * 128 + wc * 32 + fq * 8; f32x4 v0 = acc[ai][bj][m][0], v1 = acc[ai][bj][m][1];
; #pragma unroll
;                 for (int j = 0; j < 4; ++j) { const float r0 = fmaxf(v0[j], 0.f), r1 = fmaxf(v1[j], 0.f); v0[j] = r0 * r0; v1[j] = r1 * r1; }
;                 const u32x2 a = pk4(v0), b = pk4(v1); *(u32x4*)(O + (size_t)row * FF + col) = (u32x4){a.x, a.y, b.x, b.y}; } }
;     }
.LBB0_1766:
	s_mov_b32 s16, s60
	v_mov_b32_e32 v140, v144
	s_mov_b32 s17, s44
	v_mov_b32_e32 v141, v145
	s_lshl_b32 s27, s46, 8
	s_lshl_b32 s17, s17, 6
	s_add_i32 s17, s17, s27
	v_add_u32_e32 v140, s17, v140
	s_lshl_b32 s17, s26, 8
	s_lshl_b32 s16, s16, 5
	s_add_i32 s16, s16, s17
	v_lshl_add_u32 v148, v141, 3, s16
	v_ashrrev_i32_e32 v141, 31, v140
	v_max_f32_e32 v124, 0, v124
	v_lshlrev_b64 v[150:151], 14, v[140:141]
	v_max_f32_e32 v126, 0, v126
	v_max_f32_e32 v127, 0, v127
	v_mul_f32_e32 v141, v124, v124
	v_max_f32_e32 v125, 0, v125
	v_max_f32_e32 v122, 0, v122
	v_mul_f32_e32 v126, v126, v126
	v_max_f32_e32 v123, 0, v123
	v_mul_f32_e32 v127, v127, v127
	v_max_f32_e32 v128, 0, v128
	v_max_f32_e32 v124, 0, v129
	v_mul_f32_e32 v149, v125, v125
	v_mul_f32_e32 v122, v122, v122
	v_mul_f32_e32 v123, v123, v123
	v_mul_f32_e32 v128, v128, v128
	v_mul_f32_e32 v129, v124, v124
	v_cvt_pk_bf16_f32 v124, v126, v127
	v_cvt_pk_bf16_f32 v125, v128, v129
	v_cvt_pk_bf16_f32 v126, v122, v123
	v_cvt_pk_bf16_f32 v127, v141, v149
	v_ashrrev_i32_e32 v149, 31, v148
	v_lshl_add_u64 v[128:129], s[30:31], 0, v[150:151]
	v_lshlrev_b64 v[122:123], 1, v[148:149]
	v_lshl_add_u64 v[128:129], v[128:129], 0, v[122:123]
	v_max_f32_e32 v114, 0, v114
	v_max_f32_e32 v115, 0, v115
	v_max_f32_e32 v116, 0, v116
	global_store_dwordx4 v[128:129], v[124:127], off
	s_nop 1
	v_mul_f32_e32 v124, v114, v114
	v_max_f32_e32 v114, v119, v119
	v_mul_f32_e32 v119, v115, v115
	v_max_f32_e32 v115, v120, v120
	v_mul_f32_e32 v120, v116, v116
	v_max_f32_e32 v114, 0, v114
	v_max_f32_e32 v115, 0, v115
	v_max_f32_e32 v116, 0, v121
	v_max_f32_e32 v118, 0, v118
	v_mul_f32_e32 v114, v114, v114
	v_mul_f32_e32 v115, v115, v115
	v_max_f32_e32 v117, 0, v117
	v_mul_f32_e32 v116, v116, v116
	v_mul_f32_e32 v118, v118, v118
	v_mul_f32_e32 v117, v117, v117
	v_cvt_pk_bf16_f32 v114, v118, v114
	v_cvt_pk_bf16_f32 v115, v115, v116
	v_cvt_pk_bf16_f32 v116, v124, v119
	v_max_f32_e32 v106, 0, v106
	v_max_f32_e32 v107, 0, v107
	v_max_f32_e32 v108, 0, v108
	v_cvt_pk_bf16_f32 v117, v120, v117
	global_store_dwordx4 v[128:129], v[114:117], off offset:256
	s_nop 1
	v_max_f32_e32 v110, 0, v110
	v_add_u32_e32 v114, 16, v140
	v_mul_f32_e32 v116, v106, v106
	v_max_f32_e32 v106, v111, v111
	v_mul_f32_e32 v111, v107, v107
	v_max_f32_e32 v107, v112, v112
	v_mul_f32_e32 v112, v108, v108
	v_ashrrev_i32_e32 v115, 31, v114
	v_max_f32_e32 v106, 0, v106
	v_max_f32_e32 v107, 0, v107
	v_max_f32_e32 v108, 0, v113
	v_lshlrev_b64 v[114:115], 14, v[114:115]
	v_mul_f32_e32 v110, v110, v110
	v_mul_f32_e32 v106, v106, v106
	v_mul_f32_e32 v107, v107, v107
	v_mul_f32_e32 v108, v108, v108
	v_max_f32_e32 v109, 0, v109
	v_cvt_pk_bf16_f32 v106, v110, v106
	v_cvt_pk_bf16_f32 v107, v107, v108
	v_cvt_pk_bf16_f32 v108, v116, v111
	v_lshl_add_u64 v[110:111], s[30:31], 0, v[114:115]
	v_mul_f32_e32 v109, v109, v109
	v_lshl_add_u64 v[110:111], v[110:111], 0, v[122:123]
	v_max_f32_e32 v98, 0, v98
	v_max_f32_e32 v99, 0, v99
	v_max_f32_e32 v100, 0, v100
	v_cvt_pk_bf16_f32 v109, v112, v109
	global_store_dwordx4 v[110:111], v[106:109], off
	s_nop 1
	v_mul_f32_e32 v106, v98, v98
	v_max_f32_e32 v98, v103, v103
	v_mul_f32_e32 v103, v99, v99
	v_max_f32_e32 v99, v104, v104
	v_mul_f32_e32 v104, v100, v100
	v_max_f32_e32 v98, 0, v98
	v_max_f32_e32 v99, 0, v99
	v_max_f32_e32 v100, 0, v105
	v_max_f32_e32 v102, 0, v102
	v_mul_f32_e32 v98, v98, v98
	v_mul_f32_e32 v99, v99, v99
	v_max_f32_e32 v101, 0, v101
	v_mul_f32_e32 v100, v100, v100
	v_mul_f32_e32 v102, v102, v102
	v_mul_f32_e32 v101, v101, v101
	v_cvt_pk_bf16_f32 v98, v102, v98
	v_cvt_pk_bf16_f32 v99, v99, v100
	v_cvt_pk_bf16_f32 v100, v106, v103
	v_max_f32_e32 v90, 0, v90
	v_max_f32_e32 v91, 0, v91
	v_max_f32_e32 v92, 0, v92
	v_cvt_pk_bf16_f32 v101, v104, v101
	global_store_dwordx4 v[110:111], v[98:101], off offset:256
	s_nop 1
	v_max_f32_e32 v94, 0, v94
	v_add_u32_e32 v98, 32, v140
	v_mul_f32_e32 v100, v90, v90
	v_max_f32_e32 v90, v95, v95
	v_mul_f32_e32 v95, v91, v91
	v_max_f32_e32 v91, v96, v96
	v_mul_f32_e32 v96, v92, v92
	v_ashrrev_i32_e32 v99, 31, v98
	v_max_f32_e32 v90, 0, v90
	v_max_f32_e32 v91, 0, v91
	v_max_f32_e32 v92, 0, v97
	v_lshlrev_b64 v[98:99], 14, v[98:99]
	v_mul_f32_e32 v94, v94, v94
	v_mul_f32_e32 v90, v90, v90
	v_mul_f32_e32 v91, v91, v91
	v_mul_f32_e32 v92, v92, v92
	v_max_f32_e32 v93, 0, v93
	v_cvt_pk_bf16_f32 v90, v94, v90
	v_cvt_pk_bf16_f32 v91, v91, v92
	v_cvt_pk_bf16_f32 v92, v100, v95
	v_lshl_add_u64 v[94:95], s[30:31], 0, v[98:99]
	v_mul_f32_e32 v93, v93, v93
	v_lshl_add_u64 v[94:95], v[94:95], 0, v[122:123]
	v_max_f32_e32 v82, 0, v82
	v_max_f32_e32 v83, 0, v83
	v_max_f32_e32 v84, 0, v84
	v_cvt_pk_bf16_f32 v93, v96, v93
	global_store_dwordx4 v[94:95], v[90:93], off
	s_nop 1
	v_mul_f32_e32 v90, v82, v82
	v_max_f32_e32 v82, v87, v87
	v_mul_f32_e32 v87, v83, v83
	v_max_f32_e32 v83, v88, v88
	v_mul_f32_e32 v88, v84, v84
	v_max_f32_e32 v82, 0, v82
	v_max_f32_e32 v83, 0, v83
	v_max_f32_e32 v84, 0, v89
	v_max_f32_e32 v86, 0, v86
	v_mul_f32_e32 v82, v82, v82
	v_mul_f32_e32 v83, v83, v83
	v_max_f32_e32 v85, 0, v85
	v_mul_f32_e32 v84, v84, v84
	v_mul_f32_e32 v86, v86, v86
	v_mul_f32_e32 v85, v85, v85
	v_cvt_pk_bf16_f32 v82, v86, v82
	v_cvt_pk_bf16_f32 v83, v83, v84
	v_cvt_pk_bf16_f32 v84, v90, v87
	v_max_f32_e32 v74, 0, v74
	v_max_f32_e32 v75, 0, v75
	v_max_f32_e32 v76, 0, v76
	v_cvt_pk_bf16_f32 v85, v88, v85
	global_store_dwordx4 v[94:95], v[82:85], off offset:256
	s_nop 1
	v_max_f32_e32 v78, 0, v78
	v_add_u32_e32 v82, 48, v140
	v_mul_f32_e32 v84, v74, v74
	v_max_f32_e32 v74, v79, v79
	v_mul_f32_e32 v79, v75, v75
	v_max_f32_e32 v75, v80, v80
	v_mul_f32_e32 v80, v76, v76
	v_ashrrev_i32_e32 v83, 31, v82
; __device__ __forceinline__ u32x2 pk4(f32x4 v) { u32x2 w; w.x = cvt_pk_bf16(v[0], v[1]); w.y = cvt_pk_bf16(v[2], v[3]); return w; }
; #define EPI_ROWS(ai, m) _Pragma("unroll") for (int ai = 0; ai < 2; ++ai) _Pragma("unroll") for (int m = 0; m < 4; ++m)
;     __device__ __forceinline__ void operator()(const Acc& acc, const Unit& u, int wr, int wc, int fr, int fq) const {
;         EPI_ROWS(ai, m) { const int row = u.pm * 256 + ai * 128 + wr * 64 + m * 16 + fr;
; #pragma unroll
;             for (int bj = 0; bj < 2; ++bj) { const int col = u.pn * 256 + bj * 128 + wc * 32 + fq * 8; f32x4 v0 = acc[ai][bj][m][0], v1 = acc[ai][bj][m][1];
; #pragma unroll
;                 for (int j = 0; j < 4; ++j) { const float r0 = fmaxf(v0[j], 0.f), r1 = fmaxf(v1[j], 0.f); v0[j] = r0 * r0; v1[j] = r1 * r1; }
;                 const u32x2 a = pk4(v0), b = pk4(v1); *(u32x4*)(O + (size_t)row * FF + col) = (u32x4){a.x, a.y, b.x, b.y}; } }
;     }
	v_max_f32_e32 v74, 0, v74
	v_max_f32_e32 v75, 0, v75
	v_max_f32_e32 v76, 0, v81
	v_lshlrev_b64 v[82:83], 14, v[82:83]
	v_mul_f32_e32 v78, v78, v78
	v_mul_f32_e32 v74, v74, v74
	v_mul_f32_e32 v75, v75, v75
	v_mul_f32_e32 v76, v76, v76
	v_max_f32_e32 v77, 0, v77
	v_cvt_pk_bf16_f32 v74, v78, v74
	v_cvt_pk_bf16_f32 v75, v75, v76
	v_cvt_pk_bf16_f32 v76, v84, v79
	v_lshl_add_u64 v[78:79], s[30:31], 0, v[82:83]
	v_mul_f32_e32 v77, v77, v77
	v_lshl_add_u64 v[78:79], v[78:79], 0, v[122:123]
	v_max_f32_e32 v66, 0, v66
	v_max_f32_e32 v67, 0, v67
	v_max_f32_e32 v68, 0, v68
	v_cvt_pk_bf16_f32 v77, v80, v77
	global_store_dwordx4 v[78:79], v[74:77], off
	s_nop 1
	v_mul_f32_e32 v74, v66, v66
	v_max_f32_e32 v66, v71, v71
	v_mul_f32_e32 v71, v67, v67
	v_max_f32_e32 v67, v72, v72
	v_mul_f32_e32 v72, v68, v68
	v_max_f32_e32 v66, 0, v66
	v_max_f32_e32 v67, 0, v67
	v_max_f32_e32 v68, 0, v73
	v_max_f32_e32 v70, 0, v70
	v_mul_f32_e32 v66, v66, v66
	v_mul_f32_e32 v67, v67, v67
	v_max_f32_e32 v69, 0, v69
	v_mul_f32_e32 v68, v68, v68
	v_mul_f32_e32 v70, v70, v70
	v_mul_f32_e32 v69, v69, v69
	v_cvt_pk_bf16_f32 v66, v70, v66
	v_cvt_pk_bf16_f32 v67, v67, v68
	v_cvt_pk_bf16_f32 v68, v74, v71
	v_max_f32_e32 v58, 0, v58
	v_max_f32_e32 v59, 0, v59
	v_max_f32_e32 v60, 0, v60
	v_cvt_pk_bf16_f32 v69, v72, v69
	global_store_dwordx4 v[78:79], v[66:69], off offset:256
	s_nop 1
	v_max_f32_e32 v62, 0, v62
	v_add_u32_e32 v66, 0x80, v140
	v_mul_f32_e32 v68, v58, v58
	v_max_f32_e32 v58, v63, v63
	v_mul_f32_e32 v63, v59, v59
	v_max_f32_e32 v59, v64, v64
	v_mul_f32_e32 v64, v60, v60
	v_ashrrev_i32_e32 v67, 31, v66
	v_max_f32_e32 v58, 0, v58
	v_max_f32_e32 v59, 0, v59
	v_max_f32_e32 v60, 0, v65
	v_lshlrev_b64 v[66:67], 14, v[66:67]
	v_mul_f32_e32 v62, v62, v62
	v_mul_f32_e32 v58, v58, v58
	v_mul_f32_e32 v59, v59, v59
	v_mul_f32_e32 v60, v60, v60
	v_max_f32_e32 v61, 0, v61
	v_cvt_pk_bf16_f32 v58, v62, v58
	v_cvt_pk_bf16_f32 v59, v59, v60
	v_cvt_pk_bf16_f32 v60, v68, v63
	v_lshl_add_u64 v[62:63], s[30:31], 0, v[66:67]
	v_mul_f32_e32 v61, v61, v61
	v_lshl_add_u64 v[62:63], v[62:63], 0, v[122:123]
	v_max_f32_e32 v50, 0, v50
	v_max_f32_e32 v51, 0, v51
	v_max_f32_e32 v52, 0, v52
	v_cvt_pk_bf16_f32 v61, v64, v61
	global_store_dwordx4 v[62:63], v[58:61], off
	s_nop 1
	v_mul_f32_e32 v58, v50, v50
	v_max_f32_e32 v50, v55, v55
	v_mul_f32_e32 v55, v51, v51
	v_max_f32_e32 v51, v56, v56
	v_mul_f32_e32 v56, v52, v52
	v_max_f32_e32 v50, 0, v50
	v_max_f32_e32 v51, 0, v51
	v_max_f32_e32 v52, 0, v57
	v_max_f32_e32 v54, 0, v54
	v_mul_f32_e32 v50, v50, v50
	v_mul_f32_e32 v51, v51, v51
	v_max_f32_e32 v53, 0, v53
	v_mul_f32_e32 v52, v52, v52
	v_mul_f32_e32 v54, v54, v54
	v_mul_f32_e32 v53, v53, v53
	v_cvt_pk_bf16_f32 v50, v54, v50
	v_cvt_pk_bf16_f32 v51, v51, v52
	v_cvt_pk_bf16_f32 v52, v58, v55
	v_max_f32_e32 v42, 0, v42
	v_max_f32_e32 v43, 0, v43
	v_max_f32_e32 v44, 0, v44
	v_cvt_pk_bf16_f32 v53, v56, v53
	global_store_dwordx4 v[62:63], v[50:53], off offset:256
	s_nop 1
	v_max_f32_e32 v46, 0, v46
	v_add_u32_e32 v50, 0x90, v140
	v_mul_f32_e32 v52, v42, v42
	v_max_f32_e32 v42, v47, v47
	v_mul_f32_e32 v47, v43, v43
	v_max_f32_e32 v43, v48, v48
	v_mul_f32_e32 v48, v44, v44
	v_ashrrev_i32_e32 v51, 31, v50
	v_max_f32_e32 v42, 0, v42
	v_max_f32_e32 v43, 0, v43
	v_max_f32_e32 v44, 0, v49
	v_lshlrev_b64 v[50:51], 14, v[50:51]
	v_mul_f32_e32 v46, v46, v46
	v_mul_f32_e32 v42, v42, v42
	v_mul_f32_e32 v43, v43, v43
	v_mul_f32_e32 v44, v44, v44
	v_max_f32_e32 v45, 0, v45
	v_cvt_pk_bf16_f32 v42, v46, v42
	v_cvt_pk_bf16_f32 v43, v43, v44
	v_cvt_pk_bf16_f32 v44, v52, v47
	v_lshl_add_u64 v[46:47], s[30:31], 0, v[50:51]
	v_mul_f32_e32 v45, v45, v45
	v_lshl_add_u64 v[46:47], v[46:47], 0, v[122:123]
	v_max_f32_e32 v34, 0, v34
	v_max_f32_e32 v35, 0, v35
	v_max_f32_e32 v36, 0, v36
	v_cvt_pk_bf16_f32 v45, v48, v45
	global_store_dwordx4 v[46:47], v[42:45], off
	s_nop 1
	v_mul_f32_e32 v42, v34, v34
; __device__ __forceinline__ u32x2 pk4(f32x4 v) { u32x2 w; w.x = cvt_pk_bf16(v[0], v[1]); w.y = cvt_pk_bf16(v[2], v[3]); return w; }
; #define EPI_ROWS(ai, m) _Pragma("unroll") for (int ai = 0; ai < 2; ++ai) _Pragma("unroll") for (int m = 0; m < 4; ++m)
;     __device__ __forceinline__ void operator()(const Acc& acc, const Unit& u, int wr, int wc, int fr, int fq) const {
;         EPI_ROWS(ai, m) { const int row = u.pm * 256 + ai * 128 + wr * 64 + m * 16 + fr;
; #pragma unroll
;             for (int bj = 0; bj < 2; ++bj) { const int col = u.pn * 256 + bj * 128 + wc * 32 + fq * 8; f32x4 v0 = acc[ai][bj][m][0], v1 = acc[ai][bj][m][1];
; #pragma unroll
;                 for (int j = 0; j < 4; ++j) { const float r0 = fmaxf(v0[j], 0.f), r1 = fmaxf(v1[j], 0.f); v0[j] = r0 * r0; v1[j] = r1 * r1; }
;                 const u32x2 a = pk4(v0), b = pk4(v1); *(u32x4*)(O + (size_t)row * FF + col) = (u32x4){a.x, a.y, b.x, b.y}; } }
;     }
	v_max_f32_e32 v34, v39, v39
	v_mul_f32_e32 v39, v35, v35
	v_max_f32_e32 v35, v40, v40
	v_mul_f32_e32 v40, v36, v36
	v_max_f32_e32 v34, 0, v34
	v_max_f32_e32 v35, 0, v35
	v_max_f32_e32 v36, 0, v41
	v_max_f32_e32 v38, 0, v38
	v_mul_f32_e32 v34, v34, v34
	v_mul_f32_e32 v35, v35, v35
	v_max_f32_e32 v37, 0, v37
	v_mul_f32_e32 v36, v36, v36
	v_mul_f32_e32 v38, v38, v38
	v_mul_f32_e32 v37, v37, v37
	v_cvt_pk_bf16_f32 v34, v38, v34
	v_cvt_pk_bf16_f32 v35, v35, v36
	v_cvt_pk_bf16_f32 v36, v42, v39
	v_max_f32_e32 v26, 0, v26
	v_max_f32_e32 v27, 0, v27
	v_max_f32_e32 v28, 0, v28
	v_cvt_pk_bf16_f32 v37, v40, v37
	global_store_dwordx4 v[46:47], v[34:37], off offset:256
	s_nop 1
	v_max_f32_e32 v30, 0, v30
	v_add_u32_e32 v34, 0xa0, v140
	v_mul_f32_e32 v36, v26, v26
	v_max_f32_e32 v26, v31, v31
	v_mul_f32_e32 v31, v27, v27
	v_max_f32_e32 v27, v32, v32
	v_mul_f32_e32 v32, v28, v28
	v_ashrrev_i32_e32 v35, 31, v34
	v_max_f32_e32 v26, 0, v26
	v_max_f32_e32 v27, 0, v27
	v_max_f32_e32 v28, 0, v33
	v_lshlrev_b64 v[34:35], 14, v[34:35]
	v_mul_f32_e32 v30, v30, v30
	v_mul_f32_e32 v26, v26, v26
	v_mul_f32_e32 v27, v27, v27
	v_mul_f32_e32 v28, v28, v28
	v_max_f32_e32 v29, 0, v29
	v_cvt_pk_bf16_f32 v26, v30, v26
	v_cvt_pk_bf16_f32 v27, v27, v28
	v_cvt_pk_bf16_f32 v28, v36, v31
	v_lshl_add_u64 v[30:31], s[30:31], 0, v[34:35]
	v_mul_f32_e32 v29, v29, v29
	v_lshl_add_u64 v[30:31], v[30:31], 0, v[122:123]
	v_max_f32_e32 v18, 0, v18
	v_max_f32_e32 v19, 0, v19
	v_max_f32_e32 v20, 0, v20
	v_cvt_pk_bf16_f32 v29, v32, v29
	global_store_dwordx4 v[30:31], v[26:29], off
	s_nop 1
	v_mul_f32_e32 v26, v18, v18
	v_max_f32_e32 v18, v23, v23
	v_mul_f32_e32 v23, v19, v19
	v_max_f32_e32 v19, v24, v24
	v_mul_f32_e32 v24, v20, v20
	v_max_f32_e32 v18, 0, v18
	v_max_f32_e32 v19, 0, v19
	v_max_f32_e32 v20, 0, v25
	v_max_f32_e32 v22, 0, v22
	v_mul_f32_e32 v18, v18, v18
	v_mul_f32_e32 v19, v19, v19
	v_max_f32_e32 v21, 0, v21
	v_mul_f32_e32 v20, v20, v20
	v_mul_f32_e32 v22, v22, v22
	v_mul_f32_e32 v21, v21, v21
	v_cvt_pk_bf16_f32 v18, v22, v18
	v_cvt_pk_bf16_f32 v19, v19, v20
	v_cvt_pk_bf16_f32 v20, v26, v23
	v_max_f32_e32 v10, 0, v10
	v_max_f32_e32 v11, 0, v11
	v_max_f32_e32 v12, 0, v12
	v_cvt_pk_bf16_f32 v21, v24, v21
	global_store_dwordx4 v[30:31], v[18:21], off offset:256
	s_nop 1
	v_max_f32_e32 v14, 0, v14
	v_add_u32_e32 v18, 0xb0, v140
	v_mul_f32_e32 v20, v10, v10
	v_max_f32_e32 v10, v15, v15
	v_mul_f32_e32 v15, v11, v11
	v_max_f32_e32 v11, v16, v16
	v_mul_f32_e32 v16, v12, v12
	v_ashrrev_i32_e32 v19, 31, v18
	v_max_f32_e32 v10, 0, v10
	v_max_f32_e32 v11, 0, v11
	v_max_f32_e32 v12, 0, v17
	v_lshlrev_b64 v[18:19], 14, v[18:19]
	v_mul_f32_e32 v14, v14, v14
	v_mul_f32_e32 v10, v10, v10
	v_mul_f32_e32 v11, v11, v11
	v_mul_f32_e32 v12, v12, v12
	v_max_f32_e32 v13, 0, v13
	v_cvt_pk_bf16_f32 v10, v14, v10
	v_cvt_pk_bf16_f32 v11, v11, v12
	v_cvt_pk_bf16_f32 v12, v20, v15
	v_lshl_add_u64 v[14:15], s[30:31], 0, v[18:19]
	v_mul_f32_e32 v13, v13, v13
	v_lshl_add_u64 v[14:15], v[14:15], 0, v[122:123]
	v_max_f32_e32 v2, 0, v2
	v_max_f32_e32 v3, 0, v3
	v_max_f32_e32 v4, 0, v4
	v_cvt_pk_bf16_f32 v13, v16, v13
	global_store_dwordx4 v[14:15], v[10:13], off
	s_nop 1
	v_mul_f32_e32 v10, v2, v2
	v_max_f32_e32 v2, v7, v7
	v_mul_f32_e32 v7, v3, v3
	v_max_f32_e32 v3, v8, v8
	v_mul_f32_e32 v8, v4, v4
	v_max_f32_e32 v2, 0, v2
	v_max_f32_e32 v3, 0, v3
	v_max_f32_e32 v4, 0, v9
	v_max_f32_e32 v5, 0, v5
	v_max_f32_e32 v6, 0, v6
	v_mul_f32_e32 v2, v2, v2
	v_mul_f32_e32 v3, v3, v3
	v_mul_f32_e32 v4, v4, v4
	v_mul_f32_e32 v5, v5, v5
	s_andn2_b64 vcc, exec, s[2:3]
	s_mov_b64 s[2:3], -1
	v_mul_f32_e32 v6, v6, v6
	v_cvt_pk_bf16_f32 v2, v6, v2
	v_cvt_pk_bf16_f32 v3, v3, v4
	v_cvt_pk_bf16_f32 v4, v10, v7
	v_cvt_pk_bf16_f32 v5, v8, v5
	global_store_dwordx4 v[14:15], v[2:5], off offset:256
	s_cbranch_vccnz .LBB0_1759
	s_andn2_b64 vcc, exec, s[8:9]
	s_cbranch_vccnz .LBB0_1758
	s_barrier
	s_branch .LBB0_1758

; #define LAS __attribute__((address_space(3)))
; __device__ __forceinline__ unsigned pk2(float lo, float hi) { return cvt_pk_bf16(lo, hi); }
; __device__ __forceinline__ void tr_out(bf16_t* WT, int ldt, int k0, int n0, const LAS float* scr, int lane) {
;     const int c = lane & 7;
; #pragma unroll
;     for (int j = 0; j < 4; ++j) { const int n = (lane >> 3) + 8 * j; const LAS float* s = scr + (8 * c) * 33 + n;
;         u32x4 o; o.x = pk2(s[0 * 33], s[1 * 33]); o.y = pk2(s[2 * 33], s[3 * 33]); o.z = pk2(s[4 * 33], s[5 * 33]); o.w = pk2(s[6 * 33], s[7 * 33]);
;         *(u32x4*)(WT + (size_t)(n0 + n) * ldt + k0 + 8 * c) = o; }
;     asm volatile("s_waitcnt lgkmcnt(0)" ::: "memory");
; __device__ __forceinline__ void tr_job(const float* W, int K, int N, bf16_t* WT, LAS float* scr, int lane, int gw, int NGW, int& base) {
;     ...
;     while (it < nitems) {
;         tr_put(scr, lane, v);
;         const int nit = it + NGW;
;         if (nit < nitems) tr_load(W, N, 64 * (nit / nblk), 32 * (nit % nblk), lane, v);
;         tr_out(WT, K, 64 * (it / nblk), 32 * (it % nblk), scr, lane);
;         it = nit;
;     }
.LBB0_1772:
	ds_read2_b32 v[44:45], v39 offset1:33
	s_waitcnt lgkmcnt(0)
	v_cvt_pk_bf16_f32 v44, v44, v45
	ds_read2_b32 v[46:47], v39 offset0:66 offset1:99
	s_waitcnt lgkmcnt(0)
	v_cvt_pk_bf16_f32 v45, v46, v47
	ds_read2_b32 v[46:47], v39 offset0:132 offset1:165
	s_waitcnt lgkmcnt(0)
	v_cvt_pk_bf16_f32 v46, v46, v47
	ds_read2_b32 v[48:49], v39 offset0:198 offset1:231
	v_or_b32_e32 v0, s14, v38
	s_waitcnt lgkmcnt(0)
	v_cvt_pk_bf16_f32 v47, v48, v49
	v_lshlrev_b64 v[48:49], 12, v[0:1]
	v_lshl_add_u64 v[50:51], s[2:3], 0, v[34:35]
	v_lshl_add_u64 v[48:49], v[50:51], 0, v[48:49]
	global_store_dwordx4 v[48:49], v[44:47], off
	s_nop 1
	ds_read2_b32 v[44:45], v39 offset0:8 offset1:41
	v_or_b32_e32 v0, s14, v40
	s_waitcnt lgkmcnt(0)
	v_cvt_pk_bf16_f32 v44, v44, v45
	ds_read2_b32 v[46:47], v39 offset0:74 offset1:107
	s_waitcnt lgkmcnt(0)
	v_cvt_pk_bf16_f32 v45, v46, v47
	ds_read2_b32 v[46:47], v39 offset0:140 offset1:173
	s_waitcnt lgkmcnt(0)
	v_cvt_pk_bf16_f32 v46, v46, v47
	ds_read2_b32 v[48:49], v39 offset0:206 offset1:239
	v_lshlrev_b32_e32 v0, 12, v0
	s_waitcnt lgkmcnt(0)
	v_cvt_pk_bf16_f32 v47, v48, v49
	v_lshl_add_u64 v[48:49], v[50:51], 0, v[0:1]
	global_store_dwordx4 v[48:49], v[44:47], off
	s_nop 1
	ds_read2_b32 v[44:45], v39 offset0:16 offset1:49
	v_or_b32_e32 v0, s14, v41
	s_waitcnt lgkmcnt(0)
	v_cvt_pk_bf16_f32 v44, v44, v45
	ds_read2_b32 v[46:47], v39 offset0:82 offset1:115
	s_waitcnt lgkmcnt(0)
	v_cvt_pk_bf16_f32 v45, v46, v47
	ds_read2_b32 v[46:47], v39 offset0:148 offset1:181
	s_waitcnt lgkmcnt(0)
	v_cvt_pk_bf16_f32 v46, v46, v47
	ds_read2_b32 v[48:49], v39 offset0:214 offset1:247
	v_lshlrev_b32_e32 v0, 12, v0
	s_waitcnt lgkmcnt(0)
	v_cvt_pk_bf16_f32 v47, v48, v49
	v_lshl_add_u64 v[48:49], v[50:51], 0, v[0:1]
	global_store_dwordx4 v[48:49], v[44:47], off
	s_nop 1
	ds_read2_b32 v[44:45], v39 offset0:24 offset1:57
	v_or_b32_e32 v0, s14, v42
	s_waitcnt lgkmcnt(0)
	v_cvt_pk_bf16_f32 v44, v44, v45
	ds_read2_b32 v[46:47], v39 offset0:90 offset1:123
	s_waitcnt lgkmcnt(0)
	v_cvt_pk_bf16_f32 v45, v46, v47
	ds_read2_b32 v[46:47], v39 offset0:156 offset1:189
	s_waitcnt lgkmcnt(0)
	v_cvt_pk_bf16_f32 v46, v46, v47
	ds_read2_b32 v[48:49], v39 offset0:222 offset1:255
	v_lshlrev_b32_e32 v0, 12, v0
	s_waitcnt lgkmcnt(0)
	v_cvt_pk_bf16_f32 v47, v48, v49
	v_lshl_add_u64 v[48:49], v[50:51], 0, v[0:1]
	global_store_dwordx4 v[48:49], v[44:47], off
	s_addk_i32 s8, 0x400
	s_waitcnt lgkmcnt(0)
	s_add_i32 s9, s9, 0x8000
	s_add_u32 s2, s2, 0x200
	s_mov_b64 s[6:7], 0x800000
	s_addc_u32 s3, s3, 0
	v_lshl_add_u64 v[36:37], v[36:37], 0, s[6:7]
	s_andn2_b64 vcc, exec, s[4:5]
	s_cbranch_vccz .LBB0_1777
